# attention epilogues (A, B, C-pair): silu gate and softmax normalisation via v_rcp_f32*mul instead of the 11-instruction IEEE division expansion
# speedup vs baseline: 1.0167x; 1.0167x over previous
.LBB0_135:
	v_sub_f32_e32 v3, v69, v48
	v_sub_f32_e32 v64, v64, v48
	v_sub_f32_e32 v49, v49, v48
	v_exp_f32_e32 v3, v3
	v_exp_f32_e32 v76, v64
	v_exp_f32_e32 v72, v49
	v_sub_f32_e32 v49, v65, v48
	v_sub_f32_e32 v50, v50, v48
	v_exp_f32_e32 v77, v49
	v_exp_f32_e32 v73, v50
	v_sub_f32_e32 v50, v66, v48
	v_exp_f32_e32 v78, v50
	v_add_f32_e32 v64, v3, v76
	v_add_f32_e32 v64, 0, v64
	v_add_f32_e32 v49, v72, v77
	v_add_f32_e32 v49, v49, v64
	v_add_f32_e32 v50, v73, v78
	v_add_f32_e32 v49, v50, v49
	v_sub_f32_e32 v50, v51, v48
	v_exp_f32_e32 v74, v50
	v_sub_f32_e32 v50, v67, v48
	v_exp_f32_e32 v79, v50
	v_sub_f32_e32 v15, v15, v48
	v_exp_f32_e32 v15, v15
	v_sub_f32_e32 v14, v14, v48
	v_add_f32_e32 v50, v74, v79
	v_add_f32_e32 v49, v50, v49
	v_sub_f32_e32 v50, v52, v48
	v_exp_f32_e32 v75, v50
	v_sub_f32_e32 v50, v68, v48
	v_exp_f32_e32 v96, v50
	v_sub_f32_e32 v13, v13, v48
	v_exp_f32_e32 v14, v14
	v_exp_f32_e32 v108, v13
	v_add_f32_e32 v50, v75, v96
	v_add_f32_e32 v49, v50, v49
	v_sub_f32_e32 v50, v53, v48
	v_exp_f32_e32 v97, v50
	v_sub_f32_e32 v50, v63, v48
	v_exp_f32_e32 v98, v50
	v_sub_f32_e32 v12, v12, v48
	v_sub_f32_e32 v11, v11, v48
	v_exp_f32_e32 v109, v12
	v_add_f32_e32 v50, v97, v98
	v_add_f32_e32 v49, v50, v49
	v_sub_f32_e32 v50, v54, v48
	v_exp_f32_e32 v99, v50
	v_sub_f32_e32 v50, v62, v48
	v_exp_f32_e32 v100, v50
	v_exp_f32_e32 v110, v11
	v_sub_f32_e32 v10, v10, v48
	v_sub_f32_e32 v9, v9, v48
	v_add_f32_e32 v50, v99, v100
	v_add_f32_e32 v49, v50, v49
	v_sub_f32_e32 v50, v55, v48
	v_exp_f32_e32 v101, v50
	v_sub_f32_e32 v50, v61, v48
	v_exp_f32_e32 v102, v50
	v_exp_f32_e32 v111, v10
	v_exp_f32_e32 v112, v9
	v_sub_f32_e32 v8, v8, v48
	v_add_f32_e32 v50, v101, v102
	v_add_f32_e32 v49, v50, v49
	v_sub_f32_e32 v50, v56, v48
	v_exp_f32_e32 v103, v50
	v_sub_f32_e32 v50, v60, v48
	v_exp_f32_e32 v104, v50
	v_sub_f32_e32 v7, v7, v48
	v_exp_f32_e32 v113, v8
	v_exp_f32_e32 v114, v7
	v_add_f32_e32 v50, v103, v104
	v_add_f32_e32 v49, v50, v49
	v_sub_f32_e32 v50, v57, v48
	v_exp_f32_e32 v105, v50
	v_sub_f32_e32 v50, v59, v48
	v_exp_f32_e32 v106, v50
	v_sub_f32_e32 v6, v6, v48
	v_sub_f32_e32 v5, v5, v48
	v_add_f32_e32 v13, v14, v108
	v_add_f32_e32 v50, v105, v106
	v_add_f32_e32 v49, v50, v49
	v_sub_f32_e32 v50, v58, v48
	v_exp_f32_e32 v107, v50
	v_exp_f32_e32 v115, v6
	v_exp_f32_e32 v5, v5
	v_add_f32_e32 v11, v109, v110
	v_add_f32_e32 v50, v107, v15
	v_add_f32_e32 v49, v50, v49
	v_add_f32_e32 v13, v13, v49
	v_add_f32_e32 v11, v11, v13
	v_add_f32_e32 v9, v111, v112
	v_add_f32_e32 v9, v9, v11
	v_add_f32_e32 v7, v113, v114
	v_add_f32_e32 v7, v7, v9
	v_add_f32_e32 v6, v115, v5
	v_add_f32_e32 v116, v6, v7
	ds_read_b64_tr_b16 v[68:69], v151 offset:0
	ds_read_b64_tr_b16 v[70:71], v151 offset:1536
	ds_read_b64_tr_b16 v[64:65], v151 offset:64
	ds_read_b64_tr_b16 v[66:67], v151 offset:1600
	ds_read_b64_tr_b16 v[60:61], v151 offset:3072
	ds_read_b64_tr_b16 v[62:63], v151 offset:4608
	ds_read_b64_tr_b16 v[56:57], v151 offset:3136
	ds_read_b64_tr_b16 v[58:59], v151 offset:4672
	ds_read_b64_tr_b16 v[52:53], v151 offset:6144
	ds_read_b64_tr_b16 v[54:55], v151 offset:7680
	ds_read_b64_tr_b16 v[48:49], v151 offset:6208
	ds_read_b64_tr_b16 v[50:51], v151 offset:7744
	ds_read_b64_tr_b16 v[10:11], v151 offset:9216
	ds_read_b64_tr_b16 v[12:13], v151 offset:10752
	ds_read_b64_tr_b16 v[6:7], v151 offset:9280
	ds_read_b64_tr_b16 v[8:9], v151 offset:10816
	s_waitcnt lgkmcnt(0)
	v_cvt_pk_bf16_f32 v72, v3, v72
	v_cvt_pk_bf16_f32 v73, v73, v74
	v_cvt_pk_bf16_f32 v74, v75, v97
	v_cvt_pk_bf16_f32 v75, v99, v101
	v_fmac_f32_e32 v116, v2, v0
	v_mfma_f32_32x32x16_bf16 v[32:47], v[68:71], v[72:75], v[32:47]
	ds_bpermute_b32 v0, v4, v116
	s_lshl_b64 s[6:7], s[70:71], 11
	s_add_u32 s3, s86, s6
	s_addc_u32 s7, s87, s7
	s_lshl_b32 s2, s36, 1
	s_waitcnt lgkmcnt(0)
	v_add_f32_e32 v0, v116, v0
	s_add_u32 s6, s3, s2
	v_mfma_f32_32x32x16_bf16 v[16:31], v[64:67], v[72:75], v[16:31]
	v_cvt_pk_bf16_f32 v64, v103, v105
	v_cvt_pk_bf16_f32 v65, v107, v14
	v_cvt_pk_bf16_f32 v66, v109, v111
	v_cvt_pk_bf16_f32 v67, v113, v115
	v_div_scale_f32 v2, s[2:3], v0, v0, 1.0
	v_rcp_f32_e32 v3, v2
	v_mfma_f32_32x32x16_bf16 v[32:47], v[60:63], v[64:67], v[32:47]
	v_lshlrev_b32_e32 v14, 16, v93
	s_addc_u32 s7, s7, 0
	v_fma_f32 v4, -v2, v3, 1.0
	v_fmac_f32_e32 v3, v4, v3
	v_div_scale_f32 v4, vcc, 1.0, v0, 1.0
	v_mov_b32_e32 v165, v1
	v_mfma_f32_32x32x16_bf16 v[16:31], v[56:59], v[64:67], v[16:31]
	v_cvt_pk_bf16_f32 v56, v76, v77
	v_cvt_pk_bf16_f32 v57, v78, v79
	v_cvt_pk_bf16_f32 v58, v96, v98
	v_cvt_pk_bf16_f32 v59, v100, v102
	s_nop 0
	v_mfma_f32_32x32x16_bf16 v[32:47], v[52:55], v[56:59], v[32:47]
	v_mfma_f32_32x32x16_bf16 v[16:31], v[48:51], v[56:59], v[16:31]
	v_cvt_pk_bf16_f32 v48, v104, v106
	v_cvt_pk_bf16_f32 v49, v15, v108
	v_cvt_pk_bf16_f32 v50, v110, v112
	v_cvt_pk_bf16_f32 v51, v114, v5
	v_mul_f32_e32 v5, v4, v3
	v_and_b32_e32 v15, 0xffff0000, v93
	v_mfma_f32_32x32x16_bf16 v[32:47], v[10:13], v[48:51], v[32:47]
	v_lshlrev_b32_e32 v12, 16, v92
	v_and_b32_e32 v13, 0xffff0000, v92
	v_mfma_f32_32x32x16_bf16 v[16:31], v[6:9], v[48:51], v[16:31]
	v_fma_f32 v6, -v2, v5, v4
	v_fmac_f32_e32 v5, v6, v3
	v_fma_f32 v2, -v2, v5, v4
	v_div_fmas_f32 v2, v2, v3, v5
	v_div_fixup_f32 v0, v2, v0, 1.0
	s_nop 3
	v_mul_f32_e32 v4, v32, v0
	v_mul_f32_e32 v5, v36, v0
	s_nop 1
	v_permlane32_swap_b32_e32 v4, v5
	v_mul_f32_e32 v4, v12, v4
	v_mul_f32_e32 v12, 0xbfb8aa3b, v12
	v_exp_f32_e32 v12, v12
	v_mul_f32_e32 v7, v37, v0
	v_mul_f32_e32 v9, v38, v0
	v_mul_f32_e32 v11, v39, v0
	v_add_f32_e32 v12, 1.0, v12
	v_div_scale_f32 v36, s[2:3], v12, v12, v4
	v_rcp_f32_e32 v37, v36
	v_lshlrev_b32_e32 v32, 16, v94
	v_mul_f32_e32 v5, v32, v5
	v_mul_f32_e32 v6, v33, v0
	v_fma_f32 v38, -v36, v37, 1.0
	v_fmac_f32_e32 v37, v38, v37
	v_div_scale_f32 v38, vcc, v4, v12, v4
	v_mul_f32_e32 v39, v38, v37
	v_fma_f32 v48, -v36, v39, v38
	v_fmac_f32_e32 v39, v48, v37
	v_fma_f32 v36, -v36, v39, v38
	v_div_fmas_f32 v36, v36, v37, v39
	v_div_fixup_f32 v4, v36, v12, v4
	v_mul_f32_e32 v12, 0xbfb8aa3b, v32
	v_exp_f32_e32 v12, v12
	v_permlane32_swap_b32_e32 v6, v7
	v_and_b32_e32 v33, 0xffff0000, v94
	v_add_f32_e32 v12, 1.0, v12
	v_div_scale_f32 v32, s[2:3], v12, v12, v5
	v_rcp_f32_e32 v36, v32
	v_mul_f32_e32 v8, v34, v0
	s_nop 1
	v_permlane32_swap_b32_e32 v8, v9
	v_fma_f32 v37, -v32, v36, 1.0
	v_fmac_f32_e32 v36, v37, v36
	v_div_scale_f32 v37, vcc, v5, v12, v5
	v_mul_f32_e32 v38, v37, v36
	v_fma_f32 v39, -v32, v38, v37
	v_fmac_f32_e32 v38, v39, v36
	v_fma_f32 v32, -v32, v38, v37
	v_div_fmas_f32 v32, v32, v36, v38
	v_div_fixup_f32 v12, v32, v12, v5
	v_mul_f32_e32 v5, v13, v6
	v_mul_f32_e32 v6, 0xbfb8aa3b, v13
	v_exp_f32_e32 v6, v6
	v_lshlrev_b32_e32 v34, 16, v95
	v_mul_f32_e32 v10, v35, v0
	s_nop 1
	v_permlane32_swap_b32_e32 v10, v11
	v_add_f32_e32 v6, 1.0, v6
	v_div_scale_f32 v13, s[2:3], v6, v6, v5
	v_rcp_f32_e32 v32, v13
	v_and_b32_e32 v35, 0xffff0000, v95
	v_lshl_add_u64 v[2:3], s[6:7], 0, v[142:143]
	v_lshl_add_u64 v[2:3], v[2:3], 0, v[164:165]
	v_fma_f32 v36, -v13, v32, 1.0
	v_fmac_f32_e32 v32, v36, v32
	v_div_scale_f32 v36, vcc, v5, v6, v5
	v_mul_f32_e32 v37, v36, v32
	v_fma_f32 v38, -v13, v37, v36
	v_fmac_f32_e32 v37, v38, v32
	v_fma_f32 v13, -v13, v37, v36
	v_div_fmas_f32 v13, v13, v32, v37
	v_div_fixup_f32 v5, v13, v6, v5
	v_mul_f32_e32 v6, v33, v7
	v_mul_f32_e32 v7, 0xbfb8aa3b, v33
	v_exp_f32_e32 v7, v7
	v_cvt_pk_bf16_f32 v4, v4, v5
	s_nop 0
	v_add_f32_e32 v7, 1.0, v7
	v_div_scale_f32 v13, s[2:3], v7, v7, v6
	v_rcp_f32_e32 v32, v13
	s_nop 0
	v_fma_f32 v33, -v13, v32, 1.0
	v_fmac_f32_e32 v32, v33, v32
	v_div_scale_f32 v33, vcc, v6, v7, v6
	v_mul_f32_e32 v36, v33, v32
	v_fma_f32 v37, -v13, v36, v33
	v_fmac_f32_e32 v36, v37, v32
	v_fma_f32 v13, -v13, v36, v33
	v_div_fmas_f32 v13, v13, v32, v36
	v_div_fixup_f32 v6, v13, v7, v6
	v_mul_f32_e32 v7, v14, v8
	v_mul_f32_e32 v8, 0xbfb8aa3b, v14
	v_exp_f32_e32 v8, v8
	s_nop 0
	v_add_f32_e32 v8, 1.0, v8
	v_div_scale_f32 v13, s[2:3], v8, v8, v7
	v_rcp_f32_e32 v14, v13
	s_nop 0
	v_fma_f32 v32, -v13, v14, 1.0
	v_fmac_f32_e32 v14, v32, v14
	v_div_scale_f32 v32, vcc, v7, v8, v7
	v_mul_f32_e32 v33, v32, v14
	v_fma_f32 v36, -v13, v33, v32
	v_fmac_f32_e32 v33, v36, v14
	v_fma_f32 v13, -v13, v33, v32
	v_div_fmas_f32 v13, v13, v14, v33
	v_div_fixup_f32 v7, v13, v8, v7
	v_mul_f32_e32 v8, v34, v9
	v_mul_f32_e32 v9, 0xbfb8aa3b, v34
	v_exp_f32_e32 v9, v9
	s_nop 0
	v_add_f32_e32 v9, 1.0, v9
	v_div_scale_f32 v13, s[2:3], v9, v9, v8
	v_rcp_f32_e32 v14, v13
	s_nop 0
	v_fma_f32 v32, -v13, v14, 1.0
	v_fmac_f32_e32 v14, v32, v14
	v_div_scale_f32 v32, vcc, v8, v9, v8
	v_mul_f32_e32 v33, v32, v14
	v_fma_f32 v34, -v13, v33, v32
	v_fmac_f32_e32 v33, v34, v14
	v_fma_f32 v13, -v13, v33, v32
	v_div_fmas_f32 v13, v13, v14, v33
	v_div_fixup_f32 v8, v13, v9, v8
	v_mul_f32_e32 v9, v15, v10
	v_mul_f32_e32 v10, 0xbfb8aa3b, v15
	v_exp_f32_e32 v10, v10
	v_lshlrev_b32_e32 v34, 16, v91
	v_add_f32_e32 v10, 1.0, v10
	v_div_scale_f32 v13, s[2:3], v10, v10, v9
	v_rcp_f32_e32 v14, v13
	s_nop 0
	v_fma_f32 v15, -v13, v14, 1.0
	v_fmac_f32_e32 v14, v15, v14
	v_div_scale_f32 v15, vcc, v9, v10, v9
	v_mul_f32_e32 v32, v15, v14
	v_fma_f32 v33, -v13, v32, v15
	v_fmac_f32_e32 v32, v33, v14
	v_fma_f32 v13, -v13, v32, v15
	v_div_fmas_f32 v13, v13, v14, v32
	v_div_fixup_f32 v9, v13, v10, v9
	v_mul_f32_e32 v10, v35, v11
	v_mul_f32_e32 v11, 0xbfb8aa3b, v35
	v_exp_f32_e32 v11, v11
	v_cvt_pk_bf16_f32 v5, v7, v9
	v_cvt_pk_bf16_f32 v6, v12, v6
	v_lshlrev_b32_e32 v12, 16, v88
	v_add_f32_e32 v11, 1.0, v11
	v_div_scale_f32 v13, s[2:3], v11, v11, v10
	v_rcp_f32_e32 v14, v13
	v_mul_f32_e32 v9, v46, v0
	v_and_b32_e32 v35, 0xffff0000, v91
	v_fma_f32 v15, -v13, v14, 1.0
	v_fmac_f32_e32 v14, v15, v14
	v_div_scale_f32 v15, vcc, v10, v11, v10
	v_mul_f32_e32 v32, v15, v14
	v_fma_f32 v33, -v13, v32, v15
	v_fmac_f32_e32 v32, v33, v14
	v_fma_f32 v13, -v13, v32, v15
	v_div_fmas_f32 v13, v13, v14, v32
	v_div_fixup_f32 v10, v13, v11, v10
	v_cvt_pk_bf16_f32 v7, v8, v10
	global_store_dwordx4 v[2:3], v[4:7], off
	v_lshlrev_b32_e32 v32, 16, v90
	v_and_b32_e32 v13, 0xffff0000, v88
	v_mul_f32_e32 v4, v40, v0
	v_mul_f32_e32 v5, v44, v0
	s_nop 1
	v_permlane32_swap_b32_e32 v4, v5
	v_mul_f32_e32 v4, v12, v4
	v_mul_f32_e32 v12, 0xbfb8aa3b, v12
	v_exp_f32_e32 v12, v12
	v_mul_f32_e32 v5, v32, v5
	v_mul_f32_e32 v6, v41, v0
	v_mul_f32_e32 v7, v45, v0
	v_add_f32_e32 v12, 1.0, v12
	v_div_scale_f32 v36, s[2:3], v12, v12, v4
	v_rcp_f32_e32 v37, v36
	v_permlane32_swap_b32_e32 v6, v7
	v_and_b32_e32 v33, 0xffff0000, v90
	v_fma_f32 v38, -v36, v37, 1.0
	v_fmac_f32_e32 v37, v38, v37
	v_div_scale_f32 v38, vcc, v4, v12, v4
	v_mul_f32_e32 v39, v38, v37
	v_fma_f32 v40, -v36, v39, v38
	v_fmac_f32_e32 v39, v40, v37
	v_fma_f32 v36, -v36, v39, v38
	v_div_fmas_f32 v36, v36, v37, v39
	v_div_fixup_f32 v4, v36, v12, v4
	v_mul_f32_e32 v12, 0xbfb8aa3b, v32
	v_exp_f32_e32 v12, v12
	v_mul_f32_e32 v8, v42, v0
	s_nop 1
	v_permlane32_swap_b32_e32 v8, v9
	v_add_f32_e32 v12, 1.0, v12
	v_div_scale_f32 v32, s[2:3], v12, v12, v5
	v_rcp_f32_e32 v36, v32
	v_lshlrev_b32_e32 v14, 16, v89
	v_mul_f32_e32 v10, v43, v0
	v_mul_f32_e32 v11, v47, v0
	v_fma_f32 v37, -v32, v36, 1.0
	v_fmac_f32_e32 v36, v37, v36
	v_div_scale_f32 v37, vcc, v5, v12, v5
	v_mul_f32_e32 v38, v37, v36
	v_fma_f32 v39, -v32, v38, v37
	v_fmac_f32_e32 v38, v39, v36
	v_fma_f32 v32, -v32, v38, v37
	v_div_fmas_f32 v32, v32, v36, v38
	v_div_fixup_f32 v12, v32, v12, v5
	v_mul_f32_e32 v5, v13, v6
	v_mul_f32_e32 v6, 0xbfb8aa3b, v13
	v_exp_f32_e32 v6, v6
	v_permlane32_swap_b32_e32 v10, v11
	v_and_b32_e32 v15, 0xffff0000, v89
	v_add_f32_e32 v6, 1.0, v6
	v_div_scale_f32 v13, s[2:3], v6, v6, v5
	v_rcp_f32_e32 v32, v13
	s_nop 0
	v_fma_f32 v36, -v13, v32, 1.0
	v_fmac_f32_e32 v32, v36, v32
	v_div_scale_f32 v36, vcc, v5, v6, v5
	v_mul_f32_e32 v37, v36, v32
	v_fma_f32 v38, -v13, v37, v36
	v_fmac_f32_e32 v37, v38, v32
	v_fma_f32 v13, -v13, v37, v36
	v_div_fmas_f32 v13, v13, v32, v37
	v_div_fixup_f32 v5, v13, v6, v5
	v_mul_f32_e32 v6, v33, v7
	v_mul_f32_e32 v7, 0xbfb8aa3b, v33
	v_exp_f32_e32 v7, v7
	v_cvt_pk_bf16_f32 v4, v4, v5
	s_nop 0
	v_add_f32_e32 v7, 1.0, v7
	v_div_scale_f32 v13, s[2:3], v7, v7, v6
	v_rcp_f32_e32 v32, v13
	s_nop 0
	v_fma_f32 v33, -v13, v32, 1.0
	v_fmac_f32_e32 v32, v33, v32
	v_div_scale_f32 v33, vcc, v6, v7, v6
	v_mul_f32_e32 v36, v33, v32
	v_fma_f32 v37, -v13, v36, v33
	v_fmac_f32_e32 v36, v37, v32
	v_fma_f32 v13, -v13, v36, v33
	v_div_fmas_f32 v13, v13, v32, v36
	v_div_fixup_f32 v6, v13, v7, v6
	v_mul_f32_e32 v7, v14, v8
	v_mul_f32_e32 v8, 0xbfb8aa3b, v14
	v_exp_f32_e32 v8, v8
	s_nop 0
	v_add_f32_e32 v8, 1.0, v8
	v_div_scale_f32 v13, s[2:3], v8, v8, v7
	v_rcp_f32_e32 v14, v13
	s_nop 0
	v_fma_f32 v32, -v13, v14, 1.0
	v_fmac_f32_e32 v14, v32, v14
	v_div_scale_f32 v32, vcc, v7, v8, v7
	v_mul_f32_e32 v33, v32, v14
	v_fma_f32 v36, -v13, v33, v32
	v_fmac_f32_e32 v33, v36, v14
	v_fma_f32 v13, -v13, v33, v32
	v_div_fmas_f32 v13, v13, v14, v33
	v_div_fixup_f32 v7, v13, v8, v7
	v_mul_f32_e32 v8, v34, v9
	v_mul_f32_e32 v9, 0xbfb8aa3b, v34
	v_exp_f32_e32 v9, v9
	s_nop 0
	v_add_f32_e32 v9, 1.0, v9
	v_div_scale_f32 v13, s[2:3], v9, v9, v8
	v_rcp_f32_e32 v14, v13
	s_nop 0
	v_fma_f32 v32, -v13, v14, 1.0
	v_fmac_f32_e32 v14, v32, v14
	v_div_scale_f32 v32, vcc, v8, v9, v8
	v_mul_f32_e32 v33, v32, v14
	v_fma_f32 v34, -v13, v33, v32
	v_fmac_f32_e32 v33, v34, v14
	v_fma_f32 v13, -v13, v33, v32
	v_div_fmas_f32 v13, v13, v14, v33
	v_div_fixup_f32 v8, v13, v9, v8
	v_mul_f32_e32 v9, v15, v10
	v_mul_f32_e32 v10, 0xbfb8aa3b, v15
	v_exp_f32_e32 v10, v10
	s_nop 0
	v_add_f32_e32 v10, 1.0, v10
	v_div_scale_f32 v13, s[2:3], v10, v10, v9
	v_rcp_f32_e32 v14, v13
	s_nop 0
	v_fma_f32 v15, -v13, v14, 1.0
	v_fmac_f32_e32 v14, v15, v14
	v_div_scale_f32 v15, vcc, v9, v10, v9
	v_mul_f32_e32 v32, v15, v14
	v_fma_f32 v33, -v13, v32, v15
	v_fmac_f32_e32 v32, v33, v14
	v_fma_f32 v13, -v13, v32, v15
	v_div_fmas_f32 v13, v13, v14, v32
	v_div_fixup_f32 v9, v13, v10, v9
	v_mul_f32_e32 v10, v35, v11
	v_mul_f32_e32 v11, 0xbfb8aa3b, v35
	v_exp_f32_e32 v11, v11
	v_cvt_pk_bf16_f32 v5, v7, v9
	v_cvt_pk_bf16_f32 v6, v12, v6
	v_lshlrev_b32_e32 v12, 16, v84
	v_add_f32_e32 v11, 1.0, v11
	v_div_scale_f32 v13, s[2:3], v11, v11, v10
	v_rcp_f32_e32 v14, v13
	v_mul_f32_e32 v9, v22, v0
	v_fma_f32 v15, -v13, v14, 1.0
	v_fmac_f32_e32 v14, v15, v14
	v_div_scale_f32 v15, vcc, v10, v11, v10
	v_mul_f32_e32 v32, v15, v14
	v_fma_f32 v33, -v13, v32, v15
	v_fmac_f32_e32 v32, v33, v14
	v_fma_f32 v13, -v13, v32, v15
	v_div_fmas_f32 v13, v13, v14, v32
	v_div_fixup_f32 v10, v13, v11, v10
	v_cvt_pk_bf16_f32 v7, v8, v10
	global_store_dwordx4 v[2:3], v[4:7], off offset:32
	v_mul_f32_e32 v11, v23, v0
	v_and_b32_e32 v13, 0xffff0000, v84
	v_mul_f32_e32 v4, v16, v0
	v_mul_f32_e32 v5, v20, v0
	s_nop 1
	v_permlane32_swap_b32_e32 v4, v5
	v_mul_f32_e32 v4, v12, v4
	v_mul_f32_e32 v12, 0xbfb8aa3b, v12
	v_exp_f32_e32 v12, v12
	v_mul_f32_e32 v7, v21, v0
	v_lshlrev_b32_e32 v16, 16, v86
	v_mul_f32_e32 v5, v16, v5
	v_add_f32_e32 v12, 1.0, v12
	v_div_scale_f32 v20, s[2:3], v12, v12, v4
	v_rcp_f32_e32 v21, v20
	v_mul_f32_e32 v6, v17, v0
	s_nop 1
	v_permlane32_swap_b32_e32 v6, v7
	v_fma_f32 v22, -v20, v21, 1.0
	v_fmac_f32_e32 v21, v22, v21
	v_div_scale_f32 v22, vcc, v4, v12, v4
	v_mul_f32_e32 v23, v22, v21
	v_fma_f32 v32, -v20, v23, v22
	v_fmac_f32_e32 v23, v32, v21
	v_fma_f32 v20, -v20, v23, v22
	v_div_fmas_f32 v20, v20, v21, v23
	v_div_fixup_f32 v4, v20, v12, v4
	v_mul_f32_e32 v12, 0xbfb8aa3b, v16
	v_exp_f32_e32 v12, v12
	v_and_b32_e32 v17, 0xffff0000, v86
	v_mul_f32_e32 v8, v18, v0
	s_nop 1
	v_permlane32_swap_b32_e32 v8, v9
	v_add_f32_e32 v12, 1.0, v12
	v_div_scale_f32 v16, s[2:3], v12, v12, v5
	v_rcp_f32_e32 v20, v16
	v_lshlrev_b32_e32 v14, 16, v85
	v_lshlrev_b32_e32 v18, 16, v87
	v_mul_f32_e32 v10, v19, v0
	v_fma_f32 v21, -v16, v20, 1.0
	v_fmac_f32_e32 v20, v21, v20
	v_div_scale_f32 v21, vcc, v5, v12, v5
	v_mul_f32_e32 v22, v21, v20
	v_fma_f32 v23, -v16, v22, v21
	v_fmac_f32_e32 v22, v23, v20
	v_fma_f32 v16, -v16, v22, v21
	v_div_fmas_f32 v16, v16, v20, v22
	v_div_fixup_f32 v12, v16, v12, v5
	v_mul_f32_e32 v5, v13, v6
	v_mul_f32_e32 v6, 0xbfb8aa3b, v13
	v_exp_f32_e32 v6, v6
	v_permlane32_swap_b32_e32 v10, v11
	v_and_b32_e32 v15, 0xffff0000, v85
	v_add_f32_e32 v6, 1.0, v6
	v_div_scale_f32 v13, s[2:3], v6, v6, v5
	v_rcp_f32_e32 v16, v13
	v_and_b32_e32 v19, 0xffff0000, v87
	v_fma_f32 v20, -v13, v16, 1.0
	v_fmac_f32_e32 v16, v20, v16
	v_div_scale_f32 v20, vcc, v5, v6, v5
	v_mul_f32_e32 v21, v20, v16
	v_fma_f32 v22, -v13, v21, v20
	v_fmac_f32_e32 v21, v22, v16
	v_fma_f32 v13, -v13, v21, v20
	v_div_fmas_f32 v13, v13, v16, v21
	v_div_fixup_f32 v5, v13, v6, v5
	v_mul_f32_e32 v6, v17, v7
	v_mul_f32_e32 v7, 0xbfb8aa3b, v17
	v_exp_f32_e32 v7, v7
	v_cvt_pk_bf16_f32 v4, v4, v5
	s_nop 0
	v_add_f32_e32 v7, 1.0, v7
	v_div_scale_f32 v13, s[2:3], v7, v7, v6
	v_rcp_f32_e32 v16, v13
	s_nop 0
	v_fma_f32 v17, -v13, v16, 1.0
	v_fmac_f32_e32 v16, v17, v16
	v_div_scale_f32 v17, vcc, v6, v7, v6
	v_mul_f32_e32 v20, v17, v16
	v_fma_f32 v21, -v13, v20, v17
	v_fmac_f32_e32 v20, v21, v16
	v_fma_f32 v13, -v13, v20, v17
	v_div_fmas_f32 v13, v13, v16, v20
	v_div_fixup_f32 v6, v13, v7, v6
	v_mul_f32_e32 v7, v14, v8
	v_mul_f32_e32 v8, 0xbfb8aa3b, v14
	v_exp_f32_e32 v8, v8
	s_nop 0
	v_add_f32_e32 v8, 1.0, v8
	v_div_scale_f32 v13, s[2:3], v8, v8, v7
	v_rcp_f32_e32 v14, v13
	s_nop 0
	v_fma_f32 v16, -v13, v14, 1.0
	v_fmac_f32_e32 v14, v16, v14
	v_div_scale_f32 v16, vcc, v7, v8, v7
	v_mul_f32_e32 v17, v16, v14
	v_fma_f32 v20, -v13, v17, v16
	v_fmac_f32_e32 v17, v20, v14
	v_fma_f32 v13, -v13, v17, v16
	v_div_fmas_f32 v13, v13, v14, v17
	v_div_fixup_f32 v7, v13, v8, v7
	v_mul_f32_e32 v8, v18, v9
	v_mul_f32_e32 v9, 0xbfb8aa3b, v18
	v_exp_f32_e32 v9, v9
	s_nop 0
	v_add_f32_e32 v9, 1.0, v9
	v_div_scale_f32 v13, s[2:3], v9, v9, v8
	v_rcp_f32_e32 v14, v13
	s_nop 0
	v_fma_f32 v16, -v13, v14, 1.0
	v_fmac_f32_e32 v14, v16, v14
	v_div_scale_f32 v16, vcc, v8, v9, v8
	v_mul_f32_e32 v17, v16, v14
	v_fma_f32 v18, -v13, v17, v16
	v_fmac_f32_e32 v17, v18, v14
	v_fma_f32 v13, -v13, v17, v16
	v_div_fmas_f32 v13, v13, v14, v17
	v_div_fixup_f32 v8, v13, v9, v8
	v_mul_f32_e32 v9, v15, v10
	v_mul_f32_e32 v10, 0xbfb8aa3b, v15
	v_exp_f32_e32 v10, v10
	v_and_b32_e32 v18, 0xffff0000, v83
	v_add_f32_e32 v10, 1.0, v10
	v_div_scale_f32 v13, s[2:3], v10, v10, v9
	v_rcp_f32_e32 v14, v13
	s_nop 0
	v_fma_f32 v15, -v13, v14, 1.0
	v_fmac_f32_e32 v14, v15, v14
	v_div_scale_f32 v15, vcc, v9, v10, v9
	v_mul_f32_e32 v16, v15, v14
	v_fma_f32 v17, -v13, v16, v15
	v_fmac_f32_e32 v16, v17, v14
	v_fma_f32 v13, -v13, v16, v15
	v_div_fmas_f32 v13, v13, v14, v16
	v_div_fixup_f32 v9, v13, v10, v9
	v_mul_f32_e32 v10, v19, v11
	v_mul_f32_e32 v11, 0xbfb8aa3b, v19
	v_exp_f32_e32 v11, v11
	v_cvt_pk_bf16_f32 v5, v7, v9
	v_cvt_pk_bf16_f32 v6, v12, v6
	v_and_b32_e32 v12, 0xffff0000, v80
	v_add_f32_e32 v11, 1.0, v11
	v_div_scale_f32 v13, s[2:3], v11, v11, v10
	v_rcp_f32_e32 v14, v13
	v_mul_f32_e32 v9, v30, v0
	v_fma_f32 v15, -v13, v14, 1.0
	v_fmac_f32_e32 v14, v15, v14
	v_div_scale_f32 v15, vcc, v10, v11, v10
	v_mul_f32_e32 v16, v15, v14
	v_fma_f32 v17, -v13, v16, v15
	v_fmac_f32_e32 v16, v17, v14
	v_fma_f32 v13, -v13, v16, v15
	v_div_fmas_f32 v13, v13, v14, v16
	v_div_fixup_f32 v10, v13, v11, v10
	v_cvt_pk_bf16_f32 v7, v8, v10
	global_store_dwordx4 v[2:3], v[4:7], off offset:64
	v_lshlrev_b32_e32 v11, 16, v80
	v_lshlrev_b32_e32 v15, 16, v82
	v_mul_f32_e32 v4, v24, v0
	v_mul_f32_e32 v5, v28, v0
	s_nop 1
	v_permlane32_swap_b32_e32 v4, v5
	v_mul_f32_e32 v4, v11, v4
	v_mul_f32_e32 v11, 0xbfb8aa3b, v11
	v_exp_f32_e32 v11, v11
	v_mul_f32_e32 v5, v15, v5
	v_mul_f32_e32 v6, v25, v0
	v_mul_f32_e32 v7, v29, v0
	v_add_f32_e32 v11, 1.0, v11
	v_div_scale_f32 v19, s[2:3], v11, v11, v4
	v_rcp_f32_e32 v20, v19
	v_permlane32_swap_b32_e32 v6, v7
	v_and_b32_e32 v16, 0xffff0000, v82
	v_fma_f32 v21, -v19, v20, 1.0
	v_fmac_f32_e32 v20, v21, v20
	v_div_scale_f32 v21, vcc, v4, v11, v4
	v_mul_f32_e32 v22, v21, v20
	v_fma_f32 v23, -v19, v22, v21
	v_fmac_f32_e32 v22, v23, v20
	v_fma_f32 v19, -v19, v22, v21
	v_div_fmas_f32 v19, v19, v20, v22
	v_div_fixup_f32 v4, v19, v11, v4
	v_mul_f32_e32 v11, 0xbfb8aa3b, v15
	v_exp_f32_e32 v11, v11
	v_mul_f32_e32 v8, v26, v0
	s_nop 1
	v_permlane32_swap_b32_e32 v8, v9
	v_add_f32_e32 v11, 1.0, v11
	v_div_scale_f32 v15, s[2:3], v11, v11, v5
	v_rcp_f32_e32 v19, v15
	v_lshlrev_b32_e32 v13, 16, v81
	v_lshlrev_b32_e32 v17, 16, v83
	v_mul_f32_e32 v10, v27, v0
	v_fma_f32 v20, -v15, v19, 1.0
	v_fmac_f32_e32 v19, v20, v19
	v_div_scale_f32 v20, vcc, v5, v11, v5
	v_mul_f32_e32 v21, v20, v19
	v_fma_f32 v22, -v15, v21, v20
	v_fmac_f32_e32 v21, v22, v19
	v_fma_f32 v15, -v15, v21, v20
	v_div_fmas_f32 v15, v15, v19, v21
	v_div_fixup_f32 v11, v15, v11, v5
	v_mul_f32_e32 v5, v12, v6
	v_mul_f32_e32 v6, 0xbfb8aa3b, v12
	v_exp_f32_e32 v6, v6
	v_mul_f32_e32 v0, v31, v0
	s_nop 1
	v_permlane32_swap_b32_e32 v10, v0
	v_add_f32_e32 v6, 1.0, v6
	v_div_scale_f32 v12, s[2:3], v6, v6, v5
	v_rcp_f32_e32 v15, v12
	v_and_b32_e32 v14, 0xffff0000, v81
	v_mul_f32_e32 v0, v18, v0
	v_fma_f32 v19, -v12, v15, 1.0
	v_fmac_f32_e32 v15, v19, v15
	v_div_scale_f32 v19, vcc, v5, v6, v5
	v_mul_f32_e32 v20, v19, v15
	v_fma_f32 v21, -v12, v20, v19
	v_fmac_f32_e32 v20, v21, v15
	v_fma_f32 v12, -v12, v20, v19
	v_div_fmas_f32 v12, v12, v15, v20
	v_div_fixup_f32 v5, v12, v6, v5
	v_mul_f32_e32 v6, v16, v7
	v_mul_f32_e32 v7, 0xbfb8aa3b, v16
	v_exp_f32_e32 v7, v7
	v_cvt_pk_bf16_f32 v4, v4, v5
	s_nop 0
	v_add_f32_e32 v7, 1.0, v7
	s_nop 0
	v_rcp_f32_e32 v12, v7
	s_nop 0
	v_mul_f32_e32 v6, v6, v12
	v_mul_f32_e32 v7, v13, v8
	v_mul_f32_e32 v8, 0xbfb8aa3b, v13
	v_exp_f32_e32 v8, v8
	s_nop 0
	v_add_f32_e32 v8, 1.0, v8
	s_nop 0
	v_rcp_f32_e32 v12, v8
	s_nop 0
	v_mul_f32_e32 v7, v7, v12
	v_mul_f32_e32 v8, v17, v9
	v_mul_f32_e32 v9, 0xbfb8aa3b, v17
	v_exp_f32_e32 v9, v9
	s_nop 0
	v_add_f32_e32 v9, 1.0, v9
	s_nop 0
	v_rcp_f32_e32 v12, v9
	s_nop 0
	v_mul_f32_e32 v8, v8, v12
	v_mul_f32_e32 v9, v14, v10
	v_mul_f32_e32 v10, 0xbfb8aa3b, v14
	v_exp_f32_e32 v10, v10
	s_nop 0
	v_add_f32_e32 v10, 1.0, v10
	s_nop 0
	v_rcp_f32_e32 v12, v10
	s_nop 0
	v_mul_f32_e32 v9, v9, v12
	v_mul_f32_e32 v10, 0xbfb8aa3b, v18
	v_exp_f32_e32 v10, v10
	v_cvt_pk_bf16_f32 v5, v7, v9
	v_cvt_pk_bf16_f32 v6, v11, v6
	s_nop 0
	v_add_f32_e32 v10, 1.0, v10
	s_nop 0
	v_rcp_f32_e32 v12, v10
	s_nop 0
	v_mul_f32_e32 v0, v0, v12
	v_cvt_pk_bf16_f32 v7, v8, v0
	global_store_dwordx4 v[2:3], v[4:7], off offset:96

.LBB0_159:
	v_and_b32_e32 v2, 64, v199
	v_xor_b32_e32 v0, 32, v199
	v_add_u32_e32 v2, 64, v2
	v_cmp_lt_i32_e32 vcc, v0, v2
	s_xor_b64 s[6:7], s[16:17], -1
	s_waitcnt vmcnt(3)
	v_lshlrev_b32_e32 v12, 16, v92
	v_cndmask_b32_e32 v0, v199, v0, vcc
	v_lshlrev_b32_e32 v0, 2, v0
	ds_bpermute_b32 v0, v0, v117
	s_ashr_i32 s19, s18, 31
	s_lshl_b64 s[2:3], s[18:19], 11
	v_and_b32_e32 v13, 0xffff0000, v92
	v_lshlrev_b32_e32 v14, 16, v93
	s_waitcnt lgkmcnt(0)
	v_add_f32_e32 v0, v117, v0
	v_and_b32_e32 v15, 0xffff0000, v93
	s_mov_b64 s[16:17], 0
	v_rcp_f32_e32 v0, v0
	s_nop 0
	v_mul_f32_e32 v4, v32, v0
	v_mul_f32_e32 v5, v36, v0
	s_nop 1
	v_permlane32_swap_b32_e32 v4, v5
	v_mul_f32_e32 v4, v12, v4
	v_mul_f32_e32 v12, 0xbfb8aa3b, v12
	v_exp_f32_e32 v12, v12
	v_lshl_add_u64 v[2:3], v[112:113], 0, s[2:3]
	v_mul_f32_e32 v7, v37, v0
	v_mul_f32_e32 v9, v38, v0
	v_add_f32_e32 v12, 1.0, v12
	v_mul_f32_e32 v11, v39, v0
	v_lshlrev_b32_e32 v32, 16, v94
	v_mul_f32_e32 v5, v32, v5
	v_rcp_f32_e32 v36, v12
	s_nop 0
	v_mul_f32_e32 v4, v4, v36
	v_mul_f32_e32 v12, 0xbfb8aa3b, v32
	v_exp_f32_e32 v12, v12
	v_mul_f32_e32 v6, v33, v0
	s_nop 1
	v_permlane32_swap_b32_e32 v6, v7
	v_add_f32_e32 v12, 1.0, v12
	v_and_b32_e32 v33, 0xffff0000, v94
	v_mul_f32_e32 v8, v34, v0
	s_nop 1
	v_permlane32_swap_b32_e32 v8, v9
	v_rcp_f32_e32 v32, v12
	s_nop 0
	v_mul_f32_e32 v12, v5, v32
	v_mul_f32_e32 v5, v13, v6
	v_mul_f32_e32 v6, 0xbfb8aa3b, v13
	v_exp_f32_e32 v6, v6
	v_lshlrev_b32_e32 v34, 16, v95
	v_mul_f32_e32 v10, v35, v0
	s_nop 1
	v_permlane32_swap_b32_e32 v10, v11
	v_add_f32_e32 v6, 1.0, v6
	v_and_b32_e32 v35, 0xffff0000, v95
	v_rcp_f32_e32 v13, v6
	s_nop 0
	v_mul_f32_e32 v5, v5, v13
	v_mul_f32_e32 v6, v33, v7
	v_mul_f32_e32 v7, 0xbfb8aa3b, v33
	v_exp_f32_e32 v7, v7
	v_cvt_pk_bf16_f32 v4, v4, v5
	s_nop 0
	v_add_f32_e32 v7, 1.0, v7
	s_nop 0
	v_rcp_f32_e32 v13, v7
	s_nop 0
	v_mul_f32_e32 v6, v6, v13
	v_mul_f32_e32 v7, v14, v8
	v_mul_f32_e32 v8, 0xbfb8aa3b, v14
	v_exp_f32_e32 v8, v8
	s_nop 0
	v_add_f32_e32 v8, 1.0, v8
	s_nop 0
	v_rcp_f32_e32 v13, v8
	s_nop 0
	v_mul_f32_e32 v7, v7, v13
	v_mul_f32_e32 v8, v34, v9
	v_mul_f32_e32 v9, 0xbfb8aa3b, v34
	v_exp_f32_e32 v9, v9
	s_nop 0
	v_add_f32_e32 v9, 1.0, v9
	s_nop 0
	v_rcp_f32_e32 v13, v9
	s_nop 0
	v_mul_f32_e32 v8, v8, v13
	v_mul_f32_e32 v9, v15, v10
	v_mul_f32_e32 v10, 0xbfb8aa3b, v15
	v_exp_f32_e32 v10, v10
	s_waitcnt vmcnt(2)
	v_lshlrev_b32_e32 v34, 16, v91
	v_add_f32_e32 v10, 1.0, v10
	s_nop 0
	v_rcp_f32_e32 v13, v10
	s_nop 0
	v_mul_f32_e32 v9, v9, v13
	v_mul_f32_e32 v10, v35, v11
	v_mul_f32_e32 v11, 0xbfb8aa3b, v35
	v_exp_f32_e32 v11, v11
	v_cvt_pk_bf16_f32 v5, v7, v9
	v_cvt_pk_bf16_f32 v6, v12, v6
	v_lshlrev_b32_e32 v12, 16, v88
	v_add_f32_e32 v11, 1.0, v11
	v_mul_f32_e32 v9, v46, v0
	v_and_b32_e32 v35, 0xffff0000, v91
	v_rcp_f32_e32 v13, v11
	s_nop 0
	v_mul_f32_e32 v10, v10, v13
	v_cvt_pk_bf16_f32 v7, v8, v10
	global_store_dwordx4 v[2:3], v[4:7], off
	v_lshlrev_b32_e32 v32, 16, v90
	v_and_b32_e32 v13, 0xffff0000, v88
	v_mul_f32_e32 v4, v40, v0
	v_mul_f32_e32 v5, v44, v0
	s_nop 1
	v_permlane32_swap_b32_e32 v4, v5
	v_mul_f32_e32 v4, v12, v4
	v_mul_f32_e32 v12, 0xbfb8aa3b, v12
	v_exp_f32_e32 v12, v12
	v_mul_f32_e32 v5, v32, v5
	v_mul_f32_e32 v6, v41, v0
	v_mul_f32_e32 v7, v45, v0
	v_add_f32_e32 v12, 1.0, v12
	s_nop 0
	v_permlane32_swap_b32_e32 v6, v7
	v_and_b32_e32 v33, 0xffff0000, v90
	v_rcp_f32_e32 v36, v12
	s_nop 0
	v_mul_f32_e32 v4, v4, v36
	v_mul_f32_e32 v12, 0xbfb8aa3b, v32
	v_exp_f32_e32 v12, v12
	v_mul_f32_e32 v8, v42, v0
	s_nop 1
	v_permlane32_swap_b32_e32 v8, v9
	v_add_f32_e32 v12, 1.0, v12
	v_lshlrev_b32_e32 v14, 16, v89
	v_mul_f32_e32 v10, v43, v0
	v_mul_f32_e32 v11, v47, v0
	v_rcp_f32_e32 v32, v12
	s_nop 0
	v_mul_f32_e32 v12, v5, v32
	v_mul_f32_e32 v5, v13, v6
	v_mul_f32_e32 v6, 0xbfb8aa3b, v13
	v_exp_f32_e32 v6, v6
	v_permlane32_swap_b32_e32 v10, v11
	v_and_b32_e32 v15, 0xffff0000, v89
	v_add_f32_e32 v6, 1.0, v6
	s_nop 0
	v_rcp_f32_e32 v13, v6
	s_nop 0
	v_mul_f32_e32 v5, v5, v13
	v_mul_f32_e32 v6, v33, v7
	v_mul_f32_e32 v7, 0xbfb8aa3b, v33
	v_exp_f32_e32 v7, v7
	v_cvt_pk_bf16_f32 v4, v4, v5
	s_nop 0
	v_add_f32_e32 v7, 1.0, v7
	s_nop 0
	v_rcp_f32_e32 v13, v7
	s_nop 0
	v_mul_f32_e32 v6, v6, v13
	v_mul_f32_e32 v7, v14, v8
	v_mul_f32_e32 v8, 0xbfb8aa3b, v14
	v_exp_f32_e32 v8, v8
	s_nop 0
	v_add_f32_e32 v8, 1.0, v8
	s_nop 0
	v_rcp_f32_e32 v13, v8
	s_nop 0
	v_mul_f32_e32 v7, v7, v13
	v_mul_f32_e32 v8, v34, v9
	v_mul_f32_e32 v9, 0xbfb8aa3b, v34
	v_exp_f32_e32 v9, v9
	s_nop 0
	v_add_f32_e32 v9, 1.0, v9
	s_nop 0
	v_rcp_f32_e32 v13, v9
	s_nop 0
	v_mul_f32_e32 v8, v8, v13
	v_mul_f32_e32 v9, v15, v10
	v_mul_f32_e32 v10, 0xbfb8aa3b, v15
	v_exp_f32_e32 v10, v10
	s_nop 0
	v_add_f32_e32 v10, 1.0, v10
	s_nop 0
	v_rcp_f32_e32 v13, v10
	s_nop 0
	v_mul_f32_e32 v9, v9, v13
	v_mul_f32_e32 v10, v35, v11
	v_mul_f32_e32 v11, 0xbfb8aa3b, v35
	v_exp_f32_e32 v11, v11
	v_cvt_pk_bf16_f32 v5, v7, v9
	v_cvt_pk_bf16_f32 v6, v12, v6
	s_waitcnt vmcnt(2)
	v_lshlrev_b32_e32 v12, 16, v84
	v_add_f32_e32 v11, 1.0, v11
	v_mul_f32_e32 v9, v22, v0
	v_rcp_f32_e32 v13, v11
	s_nop 0
	v_mul_f32_e32 v10, v10, v13
	v_cvt_pk_bf16_f32 v7, v8, v10
	global_store_dwordx4 v[2:3], v[4:7], off offset:32
	v_mul_f32_e32 v11, v23, v0
	v_and_b32_e32 v13, 0xffff0000, v84
	v_mul_f32_e32 v4, v16, v0
	v_mul_f32_e32 v5, v20, v0
	s_nop 1
	v_permlane32_swap_b32_e32 v4, v5
	v_mul_f32_e32 v4, v12, v4
	v_mul_f32_e32 v12, 0xbfb8aa3b, v12
	v_exp_f32_e32 v12, v12
	v_mul_f32_e32 v7, v21, v0
	v_lshlrev_b32_e32 v16, 16, v86
	v_mul_f32_e32 v5, v16, v5
	v_add_f32_e32 v12, 1.0, v12
	v_mul_f32_e32 v6, v17, v0
	s_nop 1
	v_permlane32_swap_b32_e32 v6, v7
	v_rcp_f32_e32 v20, v12
	s_nop 0
	v_mul_f32_e32 v4, v4, v20
	v_mul_f32_e32 v12, 0xbfb8aa3b, v16
	v_exp_f32_e32 v12, v12
	v_and_b32_e32 v17, 0xffff0000, v86
	v_mul_f32_e32 v8, v18, v0
	s_nop 1
	v_permlane32_swap_b32_e32 v8, v9
	v_add_f32_e32 v12, 1.0, v12
	v_lshlrev_b32_e32 v14, 16, v85
	v_lshlrev_b32_e32 v18, 16, v87
	v_mul_f32_e32 v10, v19, v0
	v_rcp_f32_e32 v16, v12
	s_nop 0
	v_mul_f32_e32 v12, v5, v16
	v_mul_f32_e32 v5, v13, v6
	v_mul_f32_e32 v6, 0xbfb8aa3b, v13
	v_exp_f32_e32 v6, v6
	v_permlane32_swap_b32_e32 v10, v11
	v_and_b32_e32 v15, 0xffff0000, v85
	v_add_f32_e32 v6, 1.0, v6
	v_and_b32_e32 v19, 0xffff0000, v87
	v_rcp_f32_e32 v13, v6
	s_nop 0
	v_mul_f32_e32 v5, v5, v13
	v_mul_f32_e32 v6, v17, v7
	v_mul_f32_e32 v7, 0xbfb8aa3b, v17
	v_exp_f32_e32 v7, v7
	v_cvt_pk_bf16_f32 v4, v4, v5
	s_nop 0
	v_add_f32_e32 v7, 1.0, v7
	s_nop 0
	v_rcp_f32_e32 v13, v7
	s_nop 0
	v_mul_f32_e32 v6, v6, v13
	v_mul_f32_e32 v7, v14, v8
	v_mul_f32_e32 v8, 0xbfb8aa3b, v14
	v_exp_f32_e32 v8, v8
	s_nop 0
	v_add_f32_e32 v8, 1.0, v8
	s_nop 0
	v_rcp_f32_e32 v13, v8
	s_nop 0
	v_mul_f32_e32 v7, v7, v13
	v_mul_f32_e32 v8, v18, v9
	v_mul_f32_e32 v9, 0xbfb8aa3b, v18
	v_exp_f32_e32 v9, v9
	s_nop 0
	v_add_f32_e32 v9, 1.0, v9
	s_nop 0
	v_rcp_f32_e32 v13, v9
	s_nop 0
	v_mul_f32_e32 v8, v8, v13
	v_mul_f32_e32 v9, v15, v10
	v_mul_f32_e32 v10, 0xbfb8aa3b, v15
	v_exp_f32_e32 v10, v10
	s_waitcnt vmcnt(2)
	v_and_b32_e32 v18, 0xffff0000, v83
	v_add_f32_e32 v10, 1.0, v10
	s_nop 0
	v_rcp_f32_e32 v13, v10
	s_nop 0
	v_mul_f32_e32 v9, v9, v13
	v_mul_f32_e32 v10, v19, v11
	v_mul_f32_e32 v11, 0xbfb8aa3b, v19
	v_exp_f32_e32 v11, v11
	v_cvt_pk_bf16_f32 v5, v7, v9
	v_cvt_pk_bf16_f32 v6, v12, v6
	v_and_b32_e32 v12, 0xffff0000, v80
	v_add_f32_e32 v11, 1.0, v11
	v_mul_f32_e32 v9, v30, v0
	v_rcp_f32_e32 v13, v11
	s_nop 0
	v_mul_f32_e32 v10, v10, v13
	v_cvt_pk_bf16_f32 v7, v8, v10
	global_store_dwordx4 v[2:3], v[4:7], off offset:64
	v_lshlrev_b32_e32 v11, 16, v80
	v_lshlrev_b32_e32 v15, 16, v82
	v_mul_f32_e32 v4, v24, v0
	v_mul_f32_e32 v5, v28, v0
	s_nop 1
	v_permlane32_swap_b32_e32 v4, v5
	v_mul_f32_e32 v4, v11, v4
	v_mul_f32_e32 v11, 0xbfb8aa3b, v11
	v_exp_f32_e32 v11, v11
	v_mul_f32_e32 v5, v15, v5
	v_mul_f32_e32 v6, v25, v0
	v_mul_f32_e32 v7, v29, v0
	v_add_f32_e32 v11, 1.0, v11
	s_nop 0
	v_permlane32_swap_b32_e32 v6, v7
	v_and_b32_e32 v16, 0xffff0000, v82
	v_rcp_f32_e32 v19, v11
	s_nop 0
	v_mul_f32_e32 v4, v4, v19
	v_mul_f32_e32 v11, 0xbfb8aa3b, v15
	v_exp_f32_e32 v11, v11
	v_mul_f32_e32 v8, v26, v0
	s_nop 1
	v_permlane32_swap_b32_e32 v8, v9
	v_add_f32_e32 v11, 1.0, v11
	v_lshlrev_b32_e32 v13, 16, v81
	v_lshlrev_b32_e32 v17, 16, v83
	v_mul_f32_e32 v10, v27, v0
	v_rcp_f32_e32 v15, v11
	s_nop 0
	v_mul_f32_e32 v11, v5, v15
	v_mul_f32_e32 v5, v12, v6
	v_mul_f32_e32 v6, 0xbfb8aa3b, v12
	v_exp_f32_e32 v6, v6
	v_mul_f32_e32 v0, v31, v0
	s_nop 1
	v_permlane32_swap_b32_e32 v10, v0
	v_add_f32_e32 v6, 1.0, v6
	v_and_b32_e32 v14, 0xffff0000, v81
	v_mul_f32_e32 v0, v18, v0
	v_rcp_f32_e32 v12, v6
	s_nop 0
	v_mul_f32_e32 v5, v5, v12
	v_mul_f32_e32 v6, v16, v7
	v_mul_f32_e32 v7, 0xbfb8aa3b, v16
	v_exp_f32_e32 v7, v7
	v_cvt_pk_bf16_f32 v4, v4, v5
	s_nop 0
	v_add_f32_e32 v7, 1.0, v7
	s_nop 0
	v_rcp_f32_e32 v12, v7
	s_nop 0
	v_mul_f32_e32 v6, v6, v12
	v_mul_f32_e32 v7, v13, v8
	v_mul_f32_e32 v8, 0xbfb8aa3b, v13
	v_exp_f32_e32 v8, v8
	s_nop 0
	v_add_f32_e32 v8, 1.0, v8
	s_nop 0
	v_rcp_f32_e32 v12, v8
	s_nop 0
	v_mul_f32_e32 v7, v7, v12
	v_mul_f32_e32 v8, v17, v9
	v_mul_f32_e32 v9, 0xbfb8aa3b, v17
	v_exp_f32_e32 v9, v9
	s_nop 0
	v_add_f32_e32 v9, 1.0, v9
	s_nop 0
	v_rcp_f32_e32 v12, v9
	s_nop 0
	v_mul_f32_e32 v8, v8, v12
	v_mul_f32_e32 v9, v14, v10
	v_mul_f32_e32 v10, 0xbfb8aa3b, v14
	v_exp_f32_e32 v10, v10
	s_nop 0
	v_add_f32_e32 v10, 1.0, v10
	s_nop 0
	v_rcp_f32_e32 v12, v10
	s_nop 0
	v_mul_f32_e32 v9, v9, v12
	v_mul_f32_e32 v10, 0xbfb8aa3b, v18
	v_exp_f32_e32 v10, v10
	v_cvt_pk_bf16_f32 v5, v7, v9
	v_cvt_pk_bf16_f32 v6, v11, v6
	s_nop 0
	v_add_f32_e32 v10, 1.0, v10
	s_mov_b32 s2, 1
	s_and_b64 vcc, exec, s[6:7]
	v_rcp_f32_e32 v12, v10
	s_nop 0
	v_mul_f32_e32 v0, v0, v12
	v_cvt_pk_bf16_f32 v7, v8, v0
	global_store_dwordx4 v[2:3], v[4:7], off offset:96
	s_cbranch_vccnz .LBB0_173

.LBB0_729:
	s_mov_b64 s[16:17], 0
	s_and_b64 vcc, exec, s[14:15]
	s_mov_b64 s[0:1], 0
	s_cbranch_vccnz .LBB0_731
	v_readlane_b32 s0, v250, 29
	v_readlane_b32 s1, v250, 30
	v_lshlrev_b32_e32 v0, 1, v158
	v_lshlrev_b32_e32 v7, 16, v92
	v_lshl_add_u64 v[2:3], s[0:1], 0, v[162:163]
	v_lshl_add_u64 v[2:3], v[2:3], 0, v[0:1]
	v_mov_b32_e32 v0, v36
	s_nop 1
	v_permlane32_swap_b32_e32 v32, v0
	v_mul_f32_e32 v15, v7, v32
	v_mul_f32_e32 v7, 0xbfb8aa3b, v7
	v_exp_f32_e32 v7, v7
	v_mov_b32_e32 v4, v37
	v_lshlrev_b32_e32 v11, 16, v94
	v_mul_f32_e32 v0, v11, v0
	v_add_f32_e32 v7, 1.0, v7
	v_mul_f32_e32 v11, 0xbfb8aa3b, v11
	v_mov_b32_e32 v5, v38
	v_exp_f32_e32 v11, v11
	v_mov_b32_e32 v6, v39
	v_add_f32_e32 v11, 1.0, v11
	v_rcp_f32_e32 v32, v7
	s_nop 0
	v_mul_f32_e32 v7, v15, v32
	v_permlane32_swap_b32_e32 v33, v4
	v_and_b32_e32 v8, 0xffff0000, v92
	v_rcp_f32_e32 v15, v11
	s_nop 0
	v_mul_f32_e32 v0, v0, v15
	v_mul_f32_e32 v11, v8, v33
	v_mul_f32_e32 v8, 0xbfb8aa3b, v8
	v_exp_f32_e32 v8, v8
	v_and_b32_e32 v12, 0xffff0000, v94
	v_mul_f32_e32 v4, v12, v4
	v_permlane32_swap_b32_e32 v34, v5
	v_add_f32_e32 v8, 1.0, v8
	v_lshlrev_b32_e32 v9, 16, v93
	v_lshlrev_b32_e32 v13, 16, v95
	v_and_b32_e32 v10, 0xffff0000, v93
	v_rcp_f32_e32 v15, v8
	s_nop 0
	v_mul_f32_e32 v8, v11, v15
	v_mul_f32_e32 v11, 0xbfb8aa3b, v12
	v_exp_f32_e32 v11, v11
	v_permlane32_swap_b32_e32 v35, v6
	v_and_b32_e32 v14, 0xffff0000, v95
	v_add_f32_e32 v11, 1.0, v11
	s_nop 0
	v_rcp_f32_e32 v12, v11
	s_nop 0
	v_mul_f32_e32 v11, v4, v12
	v_mul_f32_e32 v4, v9, v34
	v_mul_f32_e32 v9, 0xbfb8aa3b, v9
	v_exp_f32_e32 v9, v9
	s_nop 0
	v_add_f32_e32 v9, 1.0, v9
	s_nop 0
	v_rcp_f32_e32 v12, v9
	s_nop 0
	v_mul_f32_e32 v9, v4, v12
	v_mul_f32_e32 v4, v13, v5
	v_mul_f32_e32 v5, 0xbfb8aa3b, v13
	v_exp_f32_e32 v5, v5
	s_nop 0
	v_add_f32_e32 v5, 1.0, v5
	s_nop 0
	v_rcp_f32_e32 v12, v5
	s_nop 0
	v_mul_f32_e32 v12, v4, v12
	v_mul_f32_e32 v5, 0xbfb8aa3b, v10
	v_exp_f32_e32 v5, v5
	v_mul_f32_e32 v4, v10, v35
	v_add_f32_e32 v5, 1.0, v5
	s_nop 0
	v_rcp_f32_e32 v10, v5
	s_nop 0
	v_mul_f32_e32 v5, v4, v10
	v_mul_f32_e32 v4, v14, v6
	v_mul_f32_e32 v6, 0xbfb8aa3b, v14
	v_exp_f32_e32 v6, v6
	s_nop 0
	v_add_f32_e32 v6, 1.0, v6
	s_nop 0
	v_rcp_f32_e32 v10, v6
	s_nop 0
	v_mul_f32_e32 v10, v4, v10
	v_cvt_pk_bf16_f32 v4, v7, v8
	v_cvt_pk_bf16_f32 v5, v9, v5
	v_cvt_pk_bf16_f32 v6, v0, v11
	v_cvt_pk_bf16_f32 v7, v12, v10
	v_mov_b32_e32 v0, v44
	global_store_dwordx4 v[2:3], v[4:7], off
	s_nop 0
	v_permlane32_swap_b32_e32 v40, v0
	v_lshlrev_b32_e32 v7, 16, v88
	v_mul_f32_e32 v15, v7, v40
	v_mul_f32_e32 v7, 0xbfb8aa3b, v7
	v_exp_f32_e32 v7, v7
	v_lshlrev_b32_e32 v11, 16, v90
	v_mul_f32_e32 v0, v11, v0
	v_mul_f32_e32 v11, 0xbfb8aa3b, v11
	v_add_f32_e32 v7, 1.0, v7
	v_exp_f32_e32 v11, v11
	v_mov_b32_e32 v4, v45
	s_nop 1
	v_permlane32_swap_b32_e32 v41, v4
	v_add_f32_e32 v11, 1.0, v11
	v_rcp_f32_e32 v32, v7
	s_nop 0
	v_mul_f32_e32 v7, v15, v32
	v_and_b32_e32 v8, 0xffff0000, v88
	v_and_b32_e32 v12, 0xffff0000, v90
	v_mul_f32_e32 v4, v12, v4
	v_rcp_f32_e32 v15, v11
	s_nop 0
	v_mul_f32_e32 v0, v0, v15
	v_mul_f32_e32 v11, v8, v41
	v_mul_f32_e32 v8, 0xbfb8aa3b, v8
	v_exp_f32_e32 v8, v8
	v_mov_b32_e32 v5, v46
	s_nop 1
	v_permlane32_swap_b32_e32 v42, v5
	v_add_f32_e32 v8, 1.0, v8
	v_lshlrev_b32_e32 v9, 16, v89
	v_lshlrev_b32_e32 v13, 16, v91
	v_and_b32_e32 v10, 0xffff0000, v89
	v_rcp_f32_e32 v15, v8
	s_nop 0
	v_mul_f32_e32 v8, v11, v15
	v_mul_f32_e32 v11, 0xbfb8aa3b, v12
	v_exp_f32_e32 v11, v11
	v_mov_b32_e32 v6, v47
	s_nop 1
	v_permlane32_swap_b32_e32 v43, v6
	v_add_f32_e32 v11, 1.0, v11
	v_and_b32_e32 v14, 0xffff0000, v91
	v_rcp_f32_e32 v12, v11
	s_nop 0
	v_mul_f32_e32 v11, v4, v12
	v_mul_f32_e32 v4, v9, v42
	v_mul_f32_e32 v9, 0xbfb8aa3b, v9
	v_exp_f32_e32 v9, v9
	s_nop 0
	v_add_f32_e32 v9, 1.0, v9
	s_nop 0
	v_rcp_f32_e32 v12, v9
	s_nop 0
	v_mul_f32_e32 v9, v4, v12
	v_mul_f32_e32 v4, v13, v5
	v_mul_f32_e32 v5, 0xbfb8aa3b, v13
	v_exp_f32_e32 v5, v5
	s_nop 0
	v_add_f32_e32 v5, 1.0, v5
	s_nop 0
	v_rcp_f32_e32 v12, v5
	s_nop 0
	v_mul_f32_e32 v12, v4, v12
	v_mul_f32_e32 v5, 0xbfb8aa3b, v10
	v_exp_f32_e32 v5, v5
	v_mul_f32_e32 v4, v10, v43
	v_add_f32_e32 v5, 1.0, v5
	s_nop 0
	v_rcp_f32_e32 v10, v5
	s_nop 0
	v_mul_f32_e32 v5, v4, v10
	v_mul_f32_e32 v4, v14, v6
	v_mul_f32_e32 v6, 0xbfb8aa3b, v14
	v_exp_f32_e32 v6, v6
	s_nop 0
	v_add_f32_e32 v6, 1.0, v6
	s_nop 0
	v_rcp_f32_e32 v10, v6
	s_nop 0
	v_mul_f32_e32 v10, v4, v10
	v_cvt_pk_bf16_f32 v4, v7, v8
	v_cvt_pk_bf16_f32 v5, v9, v5
	v_cvt_pk_bf16_f32 v6, v0, v11
	v_cvt_pk_bf16_f32 v7, v12, v10
	v_mov_b32_e32 v0, v20
	global_store_dwordx4 v[2:3], v[4:7], off offset:32
	s_nop 0
	v_permlane32_swap_b32_e32 v16, v0
	v_lshlrev_b32_e32 v7, 16, v84
	v_mul_f32_e32 v15, v7, v16
	v_mul_f32_e32 v7, 0xbfb8aa3b, v7
	v_exp_f32_e32 v7, v7
	v_mov_b32_e32 v4, v21
	v_lshlrev_b32_e32 v11, 16, v86
	v_mul_f32_e32 v0, v11, v0
	v_add_f32_e32 v7, 1.0, v7
	v_mul_f32_e32 v11, 0xbfb8aa3b, v11
	v_mov_b32_e32 v5, v22
	v_exp_f32_e32 v11, v11
	v_mov_b32_e32 v6, v23
	v_add_f32_e32 v11, 1.0, v11
	v_rcp_f32_e32 v16, v7
	s_nop 0
	v_mul_f32_e32 v7, v15, v16
	v_permlane32_swap_b32_e32 v17, v4
	v_and_b32_e32 v8, 0xffff0000, v84
	v_rcp_f32_e32 v15, v11
	s_nop 0
	v_mul_f32_e32 v0, v0, v15
	v_mul_f32_e32 v11, v8, v17
	v_mul_f32_e32 v8, 0xbfb8aa3b, v8
	v_exp_f32_e32 v8, v8
	v_and_b32_e32 v12, 0xffff0000, v86
	v_mul_f32_e32 v4, v12, v4
	v_permlane32_swap_b32_e32 v18, v5
	v_add_f32_e32 v8, 1.0, v8
	v_lshlrev_b32_e32 v9, 16, v85
	v_lshlrev_b32_e32 v13, 16, v87
	v_and_b32_e32 v10, 0xffff0000, v85
	v_rcp_f32_e32 v15, v8
	s_nop 0
	v_mul_f32_e32 v8, v11, v15
	v_mul_f32_e32 v11, 0xbfb8aa3b, v12
	v_exp_f32_e32 v11, v11
	v_permlane32_swap_b32_e32 v19, v6
	v_and_b32_e32 v14, 0xffff0000, v87
	v_add_f32_e32 v11, 1.0, v11
	s_nop 0
	v_rcp_f32_e32 v12, v11
	s_nop 0
	v_mul_f32_e32 v11, v4, v12
	v_mul_f32_e32 v4, v9, v18
	v_mul_f32_e32 v9, 0xbfb8aa3b, v9
	v_exp_f32_e32 v9, v9
	s_nop 0
	v_add_f32_e32 v9, 1.0, v9
	s_nop 0
	v_rcp_f32_e32 v12, v9
	s_nop 0
	v_mul_f32_e32 v9, v4, v12
	v_mul_f32_e32 v4, v13, v5
	v_mul_f32_e32 v5, 0xbfb8aa3b, v13
	v_exp_f32_e32 v5, v5
	s_nop 0
	v_add_f32_e32 v5, 1.0, v5
	s_nop 0
	v_rcp_f32_e32 v12, v5
	s_nop 0
	v_mul_f32_e32 v12, v4, v12
	v_mul_f32_e32 v5, 0xbfb8aa3b, v10
	v_exp_f32_e32 v5, v5
	v_mul_f32_e32 v4, v10, v19
	v_add_f32_e32 v5, 1.0, v5
	s_nop 0
	v_rcp_f32_e32 v10, v5
	s_nop 0
	v_mul_f32_e32 v5, v4, v10
	v_mul_f32_e32 v4, v14, v6
	v_mul_f32_e32 v6, 0xbfb8aa3b, v14
	v_exp_f32_e32 v6, v6
	s_nop 0
	v_add_f32_e32 v6, 1.0, v6
	s_nop 0
	v_rcp_f32_e32 v10, v6
	s_nop 0
	v_mul_f32_e32 v10, v4, v10
	v_cvt_pk_bf16_f32 v4, v7, v8
	v_cvt_pk_bf16_f32 v5, v9, v5
	v_cvt_pk_bf16_f32 v6, v0, v11
	v_mov_b32_e32 v0, v28
	v_cvt_pk_bf16_f32 v7, v12, v10
	global_store_dwordx4 v[2:3], v[4:7], off offset:64
	s_nop 0
	v_permlane32_swap_b32_e32 v24, v0
	v_lshlrev_b32_e32 v5, 16, v80
	v_mul_f32_e32 v13, v5, v24
	v_mul_f32_e32 v5, 0xbfb8aa3b, v5
	v_exp_f32_e32 v5, v5
	v_lshlrev_b32_e32 v9, 16, v82
	v_mul_f32_e32 v0, v9, v0
	v_mul_f32_e32 v9, 0xbfb8aa3b, v9
	v_add_f32_e32 v5, 1.0, v5
	v_exp_f32_e32 v9, v9
	v_mov_b32_e32 v2, v29
	s_nop 1
	v_permlane32_swap_b32_e32 v25, v2
	v_add_f32_e32 v9, 1.0, v9
	v_rcp_f32_e32 v14, v5
	s_nop 0
	v_mul_f32_e32 v5, v13, v14
	v_and_b32_e32 v6, 0xffff0000, v80
	v_and_b32_e32 v10, 0xffff0000, v82
	v_mul_f32_e32 v2, v10, v2
	v_rcp_f32_e32 v13, v9
	s_nop 0
	v_mul_f32_e32 v0, v0, v13
	v_mul_f32_e32 v9, v6, v25
	v_mul_f32_e32 v6, 0xbfb8aa3b, v6
	v_exp_f32_e32 v6, v6
	v_mov_b32_e32 v3, v30
	s_nop 1
	v_permlane32_swap_b32_e32 v26, v3
	v_add_f32_e32 v6, 1.0, v6
	v_lshlrev_b32_e32 v7, 16, v81
	v_lshlrev_b32_e32 v11, 16, v83
	v_and_b32_e32 v8, 0xffff0000, v81
	v_rcp_f32_e32 v13, v6
	s_nop 0
	v_mul_f32_e32 v6, v9, v13
	v_mul_f32_e32 v9, 0xbfb8aa3b, v10
	v_exp_f32_e32 v9, v9
	v_mov_b32_e32 v4, v31
	s_nop 1
	v_permlane32_swap_b32_e32 v27, v4
	v_add_f32_e32 v9, 1.0, v9
	v_and_b32_e32 v12, 0xffff0000, v83
	v_rcp_f32_e32 v10, v9
	s_nop 0
	v_mul_f32_e32 v9, v2, v10
	v_mul_f32_e32 v2, v7, v26
	v_mul_f32_e32 v7, 0xbfb8aa3b, v7
	v_exp_f32_e32 v7, v7
	s_nop 0
	v_add_f32_e32 v7, 1.0, v7
	s_nop 0
	v_rcp_f32_e32 v10, v7
	s_nop 0
	v_mul_f32_e32 v7, v2, v10
	v_mul_f32_e32 v2, v11, v3
	v_mul_f32_e32 v3, 0xbfb8aa3b, v11
	v_exp_f32_e32 v3, v3
	s_nop 0
	v_add_f32_e32 v3, 1.0, v3
	s_nop 0
	v_rcp_f32_e32 v10, v3
	s_nop 0
	v_mul_f32_e32 v10, v2, v10
	v_mul_f32_e32 v3, 0xbfb8aa3b, v8
	v_exp_f32_e32 v3, v3
	v_mul_f32_e32 v2, v8, v27
	v_add_f32_e32 v3, 1.0, v3
	s_nop 0
	v_rcp_f32_e32 v8, v3
	s_nop 0
	v_mul_f32_e32 v3, v2, v8
	v_mul_f32_e32 v2, v12, v4
	v_mul_f32_e32 v4, 0xbfb8aa3b, v12
	v_exp_f32_e32 v4, v4
	s_nop 0
	v_add_f32_e32 v4, 1.0, v4
	s_mov_b64 s[0:1], -1
	v_rcp_f32_e32 v8, v4
	s_nop 0
	v_mul_f32_e32 v8, v2, v8
	v_cvt_pk_bf16_f32 v2, v5, v6
	v_cvt_pk_bf16_f32 v3, v7, v3
	v_cvt_pk_bf16_f32 v4, v0, v9
	v_cvt_pk_bf16_f32 v5, v10, v8

.LBB0_804:
	v_readlane_b32 s45, v251, 52
	s_and_b64 vcc, exec, s[14:15]
	s_cbranch_vccnz .LBB0_806
	v_and_b32_e32 v2, 64, v199
	v_xor_b32_e32 v0, 32, v199
	v_add_u32_e32 v2, 64, v2
	v_cmp_lt_i32_e32 vcc, v0, v2
	v_lshlrev_b32_e32 v12, 16, v92
	v_and_b32_e32 v13, 0xffff0000, v92
	v_cndmask_b32_e32 v0, v199, v0, vcc
	v_lshlrev_b32_e32 v0, 2, v0
	ds_bpermute_b32 v0, v0, v224
	v_lshlrev_b32_e32 v14, 16, v93
	v_and_b32_e32 v15, 0xffff0000, v93
	s_waitcnt lgkmcnt(0)
	v_add_f32_e32 v0, v224, v0
	v_readlane_b32 s0, v250, 29
	v_readlane_b32 s1, v250, 30
	v_rcp_f32_e32 v4, v0
	s_nop 0
	v_lshl_add_u64 v[2:3], s[0:1], 0, v[162:163]
	v_lshlrev_b32_e32 v0, 1, v158
	v_lshl_add_u64 v[2:3], v[2:3], 0, v[0:1]
	v_mul_f32_e32 v0, v32, v4
	v_mul_f32_e32 v5, v36, v4
	s_nop 1
	v_permlane32_swap_b32_e32 v0, v5
	v_mul_f32_e32 v0, v12, v0
	v_mul_f32_e32 v12, 0xbfb8aa3b, v12
	v_exp_f32_e32 v12, v12
	v_mul_f32_e32 v7, v37, v4
	v_mul_f32_e32 v9, v38, v4
	v_mul_f32_e32 v11, v39, v4
	v_add_f32_e32 v12, 1.0, v12
	v_lshlrev_b32_e32 v32, 16, v94
	v_mul_f32_e32 v5, v32, v5
	v_mul_f32_e32 v6, v33, v4
	v_rcp_f32_e32 v36, v12
	s_nop 0
	v_mul_f32_e32 v0, v0, v36
	v_mul_f32_e32 v12, 0xbfb8aa3b, v32
	v_exp_f32_e32 v12, v12
	v_permlane32_swap_b32_e32 v6, v7
	v_mul_f32_e32 v6, v13, v6
	v_add_f32_e32 v12, 1.0, v12
	v_and_b32_e32 v33, 0xffff0000, v94
	v_mul_f32_e32 v7, v33, v7
	v_mul_f32_e32 v8, v34, v4
	v_rcp_f32_e32 v32, v12
	s_nop 0
	v_mul_f32_e32 v5, v5, v32
	v_mul_f32_e32 v12, 0xbfb8aa3b, v13
	v_exp_f32_e32 v12, v12
	v_permlane32_swap_b32_e32 v8, v9
	v_lshlrev_b32_e32 v34, 16, v95
	v_add_f32_e32 v12, 1.0, v12
	v_mul_f32_e32 v10, v35, v4
	s_nop 1
	v_permlane32_swap_b32_e32 v10, v11
	v_rcp_f32_e32 v13, v12
	s_nop 0
	v_mul_f32_e32 v6, v6, v13
	v_mul_f32_e32 v12, 0xbfb8aa3b, v33
	v_exp_f32_e32 v12, v12
	v_and_b32_e32 v35, 0xffff0000, v95
	v_cvt_pk_bf16_f32 v6, v0, v6
	v_mul_f32_e32 v0, v40, v4
	v_add_f32_e32 v12, 1.0, v12
	s_nop 0
	v_rcp_f32_e32 v13, v12
	s_nop 0
	v_mul_f32_e32 v12, v7, v13
	v_mul_f32_e32 v7, v14, v8
	v_mul_f32_e32 v8, 0xbfb8aa3b, v14
	v_exp_f32_e32 v8, v8
	s_nop 0
	v_add_f32_e32 v8, 1.0, v8
	s_nop 0
	v_rcp_f32_e32 v13, v8
	s_nop 0
	v_mul_f32_e32 v7, v7, v13
	v_mul_f32_e32 v8, v34, v9
	v_mul_f32_e32 v9, 0xbfb8aa3b, v34
	v_exp_f32_e32 v9, v9
	s_nop 0
	v_add_f32_e32 v9, 1.0, v9
	s_nop 0
	v_rcp_f32_e32 v13, v9
	s_nop 0
	v_mul_f32_e32 v9, v8, v13
	v_mul_f32_e32 v8, v15, v10
	v_mul_f32_e32 v10, 0xbfb8aa3b, v15
	v_exp_f32_e32 v10, v10
	v_lshlrev_b32_e32 v34, 16, v91
	v_add_f32_e32 v10, 1.0, v10
	s_nop 0
	v_rcp_f32_e32 v13, v10
	s_nop 0
	v_mul_f32_e32 v8, v8, v13
	v_mul_f32_e32 v10, v35, v11
	v_mul_f32_e32 v11, 0xbfb8aa3b, v35
	v_exp_f32_e32 v11, v11
	v_cvt_pk_bf16_f32 v7, v7, v8
	v_cvt_pk_bf16_f32 v8, v5, v12
	v_mul_f32_e32 v5, v44, v4
	s_nop 1
	v_permlane32_swap_b32_e32 v0, v5
	v_lshlrev_b32_e32 v12, 16, v88
	v_add_f32_e32 v11, 1.0, v11
	v_mul_f32_e32 v0, v12, v0
	v_mul_f32_e32 v12, 0xbfb8aa3b, v12
	v_exp_f32_e32 v12, v12
	v_and_b32_e32 v35, 0xffff0000, v91
	v_add_f32_e32 v12, 1.0, v12
	v_lshlrev_b32_e32 v32, 16, v90
	v_rcp_f32_e32 v36, v12
	s_nop 0
	v_mul_f32_e32 v0, v0, v36
	v_mul_f32_e32 v12, 0xbfb8aa3b, v32
	v_exp_f32_e32 v12, v12
	v_mul_f32_e32 v5, v32, v5
	v_rcp_f32_e32 v13, v11
	s_nop 0
	v_mul_f32_e32 v10, v10, v13
	v_and_b32_e32 v13, 0xffff0000, v88
	v_add_f32_e32 v12, 1.0, v12
	v_cvt_pk_bf16_f32 v9, v9, v10
	global_store_dwordx4 v[2:3], v[6:9], off
	v_and_b32_e32 v33, 0xffff0000, v90
	v_rcp_f32_e32 v32, v12
	s_nop 0
	v_mul_f32_e32 v5, v5, v32
	v_mul_f32_e32 v12, 0xbfb8aa3b, v13
	v_exp_f32_e32 v12, v12
	v_mul_f32_e32 v6, v41, v4
	v_mul_f32_e32 v7, v45, v4
	s_nop 1
	v_permlane32_swap_b32_e32 v6, v7
	v_mul_f32_e32 v6, v13, v6
	v_add_f32_e32 v12, 1.0, v12
	v_mul_f32_e32 v7, v33, v7
	v_mul_f32_e32 v8, v42, v4
	v_mul_f32_e32 v9, v46, v4
	v_rcp_f32_e32 v13, v12
	s_nop 0
	v_mul_f32_e32 v6, v6, v13
	v_mul_f32_e32 v12, 0xbfb8aa3b, v33
	v_exp_f32_e32 v12, v12
	v_permlane32_swap_b32_e32 v8, v9
	v_lshlrev_b32_e32 v14, 16, v89
	v_add_f32_e32 v12, 1.0, v12
	v_mul_f32_e32 v10, v43, v4
	v_mul_f32_e32 v11, v47, v4
	s_nop 1
	v_permlane32_swap_b32_e32 v10, v11
	v_rcp_f32_e32 v13, v12
	s_nop 0
	v_mul_f32_e32 v12, v7, v13
	v_mul_f32_e32 v7, v14, v8
	v_mul_f32_e32 v8, 0xbfb8aa3b, v14
	v_exp_f32_e32 v8, v8
	v_and_b32_e32 v15, 0xffff0000, v89
	v_cvt_pk_bf16_f32 v6, v0, v6
	v_mul_f32_e32 v0, v16, v4
	v_add_f32_e32 v8, 1.0, v8
	v_lshlrev_b32_e32 v16, 16, v86
	v_rcp_f32_e32 v13, v8
	s_nop 0
	v_mul_f32_e32 v7, v7, v13
	v_mul_f32_e32 v8, v34, v9
	v_mul_f32_e32 v9, 0xbfb8aa3b, v34
	v_exp_f32_e32 v9, v9
	s_nop 0
	v_add_f32_e32 v9, 1.0, v9
	s_nop 0
	v_rcp_f32_e32 v13, v9
	s_nop 0
	v_mul_f32_e32 v9, v8, v13
	v_mul_f32_e32 v8, v15, v10
	v_mul_f32_e32 v10, 0xbfb8aa3b, v15
	v_exp_f32_e32 v10, v10
	s_nop 0
	v_add_f32_e32 v10, 1.0, v10
	s_nop 0
	v_rcp_f32_e32 v13, v10
	s_nop 0
	v_mul_f32_e32 v8, v8, v13
	v_mul_f32_e32 v10, v35, v11
	v_mul_f32_e32 v11, 0xbfb8aa3b, v35
	v_exp_f32_e32 v11, v11
	v_cvt_pk_bf16_f32 v7, v7, v8
	v_cvt_pk_bf16_f32 v8, v5, v12
	v_mul_f32_e32 v5, v20, v4
	v_add_f32_e32 v11, 1.0, v11
	s_nop 0
	v_permlane32_swap_b32_e32 v0, v5
	v_lshlrev_b32_e32 v12, 16, v84
	v_mul_f32_e32 v0, v12, v0
	v_mul_f32_e32 v12, 0xbfb8aa3b, v12
	v_exp_f32_e32 v12, v12
	s_nop 0
	v_add_f32_e32 v12, 1.0, v12
	v_rcp_f32_e32 v13, v11
	s_nop 0
	v_mul_f32_e32 v10, v10, v13
	v_cvt_pk_bf16_f32 v9, v9, v10
	global_store_dwordx4 v[2:3], v[6:9], off offset:32
	v_mul_f32_e32 v11, v23, v4
	v_mul_f32_e32 v5, v16, v5
	v_mul_f32_e32 v7, v21, v4
	v_mul_f32_e32 v9, v22, v4
	v_and_b32_e32 v13, 0xffff0000, v84
	v_mul_f32_e32 v6, v17, v4
	v_rcp_f32_e32 v20, v12
	s_nop 0
	v_mul_f32_e32 v0, v0, v20
	v_mul_f32_e32 v12, 0xbfb8aa3b, v16
	v_exp_f32_e32 v12, v12
	v_permlane32_swap_b32_e32 v6, v7
	v_mul_f32_e32 v6, v13, v6
	v_add_f32_e32 v12, 1.0, v12
	v_and_b32_e32 v17, 0xffff0000, v86
	v_mul_f32_e32 v7, v17, v7
	v_mul_f32_e32 v8, v18, v4
	v_rcp_f32_e32 v16, v12
	s_nop 0
	v_mul_f32_e32 v5, v5, v16
	v_mul_f32_e32 v12, 0xbfb8aa3b, v13
	v_exp_f32_e32 v12, v12
	v_permlane32_swap_b32_e32 v8, v9
	v_lshlrev_b32_e32 v14, 16, v85
	v_add_f32_e32 v12, 1.0, v12
	v_lshlrev_b32_e32 v18, 16, v87
	v_mul_f32_e32 v10, v19, v4
	s_nop 1
	v_permlane32_swap_b32_e32 v10, v11
	v_rcp_f32_e32 v13, v12
	s_nop 0
	v_mul_f32_e32 v6, v6, v13
	v_mul_f32_e32 v12, 0xbfb8aa3b, v17
	v_exp_f32_e32 v12, v12
	v_and_b32_e32 v15, 0xffff0000, v85
	v_and_b32_e32 v19, 0xffff0000, v87
	v_cvt_pk_bf16_f32 v6, v0, v6
	v_add_f32_e32 v12, 1.0, v12
	v_mul_f32_e32 v0, v24, v4
	v_rcp_f32_e32 v13, v12
	s_nop 0
	v_mul_f32_e32 v12, v7, v13
	v_mul_f32_e32 v7, v14, v8
	v_mul_f32_e32 v8, 0xbfb8aa3b, v14
	v_exp_f32_e32 v8, v8
	s_nop 0
	v_add_f32_e32 v8, 1.0, v8
	s_nop 0
	v_rcp_f32_e32 v13, v8
	s_nop 0
	v_mul_f32_e32 v7, v7, v13
	v_mul_f32_e32 v8, v18, v9
	v_mul_f32_e32 v9, 0xbfb8aa3b, v18
	v_exp_f32_e32 v9, v9
	s_nop 0
	v_add_f32_e32 v9, 1.0, v9
	s_nop 0
	v_rcp_f32_e32 v13, v9
	s_nop 0
	v_mul_f32_e32 v9, v8, v13
	v_mul_f32_e32 v8, v15, v10
	v_mul_f32_e32 v10, 0xbfb8aa3b, v15
	v_exp_f32_e32 v10, v10
	s_nop 0
	v_add_f32_e32 v10, 1.0, v10
	s_nop 0
	v_rcp_f32_e32 v13, v10
	s_nop 0
	v_mul_f32_e32 v8, v8, v13
	v_mul_f32_e32 v10, v19, v11
	v_mul_f32_e32 v11, 0xbfb8aa3b, v19
	v_exp_f32_e32 v11, v11
	v_cvt_pk_bf16_f32 v7, v7, v8
	v_cvt_pk_bf16_f32 v8, v5, v12
	v_mul_f32_e32 v5, v29, v4
	v_add_f32_e32 v11, 1.0, v11
	v_and_b32_e32 v12, 0xffff0000, v81
	v_rcp_f32_e32 v13, v11
	s_nop 0
	v_mul_f32_e32 v10, v10, v13
	v_cvt_pk_bf16_f32 v9, v9, v10
	global_store_dwordx4 v[2:3], v[6:9], off offset:64
	v_mul_f32_e32 v2, v28, v4
	s_nop 1
	v_permlane32_swap_b32_e32 v0, v2
	v_lshlrev_b32_e32 v9, 16, v80
	v_mul_f32_e32 v0, v9, v0
	v_mul_f32_e32 v9, 0xbfb8aa3b, v9
	v_exp_f32_e32 v9, v9
	v_lshlrev_b32_e32 v13, 16, v82
	v_mul_f32_e32 v2, v13, v2
	v_mul_f32_e32 v3, v25, v4
	v_add_f32_e32 v9, 1.0, v9
	s_nop 0
	v_permlane32_swap_b32_e32 v3, v5
	v_and_b32_e32 v10, 0xffff0000, v80
	v_rcp_f32_e32 v17, v9
	s_nop 0
	v_mul_f32_e32 v0, v0, v17
	v_mul_f32_e32 v9, 0xbfb8aa3b, v13
	v_exp_f32_e32 v9, v9
	v_and_b32_e32 v14, 0xffff0000, v82
	v_mul_f32_e32 v6, v26, v4
	v_mul_f32_e32 v7, v30, v4
	v_add_f32_e32 v9, 1.0, v9
	s_nop 0
	v_permlane32_swap_b32_e32 v6, v7
	v_lshlrev_b32_e32 v11, 16, v81
	v_rcp_f32_e32 v13, v9
	s_nop 0
	v_mul_f32_e32 v9, v2, v13
	v_mul_f32_e32 v2, v10, v3
	v_mul_f32_e32 v3, 0xbfb8aa3b, v10
	v_exp_f32_e32 v3, v3
	v_lshlrev_b32_e32 v15, 16, v83
	v_mul_f32_e32 v8, v27, v4
	v_mul_f32_e32 v4, v31, v4
	v_add_f32_e32 v3, 1.0, v3
	s_nop 0
	v_permlane32_swap_b32_e32 v8, v4
	v_and_b32_e32 v16, 0xffff0000, v83
	v_rcp_f32_e32 v10, v3
	s_nop 0
	v_mul_f32_e32 v2, v2, v10
	v_mul_f32_e32 v3, v14, v5
	v_mul_f32_e32 v5, 0xbfb8aa3b, v14
	v_exp_f32_e32 v5, v5
	v_mul_f32_e32 v4, v16, v4
	v_cvt_pk_bf16_f32 v2, v0, v2
	v_add_f32_e32 v5, 1.0, v5
	s_nop 0
	v_rcp_f32_e32 v10, v5
	s_nop 0
	v_mul_f32_e32 v5, v3, v10
	v_mul_f32_e32 v3, v11, v6
	v_mul_f32_e32 v6, 0xbfb8aa3b, v11
	v_exp_f32_e32 v6, v6
	s_nop 0
	v_add_f32_e32 v6, 1.0, v6
	s_nop 0
	v_rcp_f32_e32 v10, v6
	s_nop 0
	v_mul_f32_e32 v3, v3, v10
	v_mul_f32_e32 v6, v15, v7
	v_mul_f32_e32 v7, 0xbfb8aa3b, v15
	v_exp_f32_e32 v7, v7
	s_nop 0
	v_add_f32_e32 v7, 1.0, v7
	s_nop 0
	v_rcp_f32_e32 v10, v7
	s_nop 0
	v_mul_f32_e32 v6, v6, v10
	v_mul_f32_e32 v7, v12, v8
	v_mul_f32_e32 v8, 0xbfb8aa3b, v12
	v_exp_f32_e32 v8, v8
	s_nop 0
	v_add_f32_e32 v8, 1.0, v8
	s_nop 0
	v_rcp_f32_e32 v10, v8
	s_nop 0
	v_mul_f32_e32 v7, v7, v10
	v_mul_f32_e32 v8, 0xbfb8aa3b, v16
	v_exp_f32_e32 v8, v8
	v_cvt_pk_bf16_f32 v3, v3, v7
	s_nop 0
	v_add_f32_e32 v8, 1.0, v8
	s_mov_b64 s[0:1], -1
	v_rcp_f32_e32 v10, v8
	s_nop 0
	v_mul_f32_e32 v8, v4, v10
	v_cvt_pk_bf16_f32 v4, v9, v5
	v_cvt_pk_bf16_f32 v5, v6, v8
